# kprio4 + waves 0-3 sleep 512 cycles at the start of each key tile's compute in the three flash-attention loops (software stagger)
# baseline (speedup 1.0000x reference)
; template <int MODE>
; __device__ __forceinline__ void flash_unit(ArgsP A, int l, int b, int h, int qb, unsigned char* lds) {
;     ...
;     for (int t = 0; t < ntile; ++t) {
;         {
;             const int later = (ntile - 1 - t) < (NBUF - 2) ? (ntile - 1 - t) : (NBUF - 2);
;             if (later <= 0) asm volatile("s_waitcnt vmcnt(0) lgkmcnt(0)\n\ts_barrier" ::: "memory");
;             else if (later == 1) asm volatile("s_waitcnt vmcnt(%0) lgkmcnt(0)\n\ts_barrier" :: "n"(OPS) : "memory");
;             else asm volatile("s_waitcnt vmcnt(%0) lgkmcnt(0)\n\ts_barrier" :: "n"(2 * OPS) : "memory");
;         }
;         if (t + NBUF - 1 < ntile) dma_tile(t + NBUF - 1);
;         if (t <= tlast) {
;             const int slot = t % NBUF; const unsigned char* kb_ = lds + slot * KBYTES; const unsigned char* vb_ = lds + NBUF * KBYTES + slot * VBYTES;
.LBB0_753:
	v_readfirstlane_b32 s100, v238
	s_cmp_lt_u32 s100, 0x100
	s_cbranch_scc0 .Lslp_753
	s_sleep 8
